# v51 + XCD-local barrier: no-return arrival, delayed and slower polling of the arrival counter against a tracked target
# baseline (speedup 1.0000x reference)
.LBB0_426:
	s_and_b64 vcc, exec, s[38:39]
	s_cbranch_vccz .LBB0_446
	s_waitcnt vmcnt(0)
	s_barrier
	s_mov_b64 s[38:39], exec
	v_readlane_b32 s20, v254, 3
	v_readlane_b32 s21, v254, 4
	s_and_b64 s[20:21], s[38:39], s[20:21]
	s_mov_b64 exec, s[20:21]
	s_cbranch_execz .LBB0_445
	buffer_inv sc1
	v_readlane_b32 s20, v254, 61
	v_readlane_b32 s21, v254, 62
	v_readlane_b32 s6, v255, 60
	v_mov_b32_e32 v0, 1
	s_nop 3
	s_add_i32 s6, s6, 32
	global_atomic_add v49, v0, s[20:21]
	v_writelane_b32 v255, s6, 60
	s_sleep 6
.Llb_poll0:
	global_load_dword v1, v49, s[20:21] sc1
	s_waitcnt vmcnt(0)
	v_readfirstlane_b32 s26, v1
	s_nop 0
	s_cmp_ge_u32 s26, s6
	s_cbranch_scc1 .Llb_done0
	s_sleep 3
	s_branch .Llb_poll0

.LBB0_752:
	s_and_b64 vcc, exec, s[40:41]
	s_cbranch_vccz .LBB0_772
	s_waitcnt vmcnt(0)
	s_barrier
	s_mov_b64 s[40:41], exec
	v_readlane_b32 s8, v254, 3
	v_readlane_b32 s9, v254, 4
	s_and_b64 s[8:9], s[40:41], s[8:9]
	s_mov_b64 exec, s[8:9]
	s_cbranch_execz .LBB0_771
	buffer_inv sc1
	v_readlane_b32 s20, v254, 61
	v_readlane_b32 s21, v254, 62
	v_readlane_b32 s6, v255, 60
	v_mov_b32_e32 v0, 1
	s_nop 3
	s_add_i32 s6, s6, 32
	global_atomic_add v49, v0, s[20:21]
	v_writelane_b32 v255, s6, 60
	s_sleep 6
.Llb_poll2:
	global_load_dword v1, v49, s[20:21] sc1
	s_waitcnt vmcnt(0)
	v_readfirstlane_b32 s9, v1
	s_nop 0
	s_cmp_ge_u32 s9, s6
	s_cbranch_scc1 .Llb_done2
	s_sleep 3
	s_branch .Llb_poll2

.LBB0_1008:
	s_and_b64 vcc, exec, s[40:41]
	s_cbranch_vccz .LBB0_1028
	s_waitcnt vmcnt(0)
	s_barrier
	s_mov_b64 s[40:41], exec
	v_readlane_b32 s6, v254, 3
	v_readlane_b32 s7, v254, 4
	s_and_b64 s[6:7], s[40:41], s[6:7]
	s_mov_b64 exec, s[6:7]
	s_cbranch_execz .LBB0_1027
	buffer_inv sc1
	v_readlane_b32 s20, v254, 61
	v_readlane_b32 s21, v254, 62
	v_readlane_b32 s6, v255, 60
	v_mov_b32_e32 v0, 1
	s_nop 3
	s_add_i32 s6, s6, 32
	global_atomic_add v49, v0, s[20:21]
	v_writelane_b32 v255, s6, 60
	s_sleep 6

.LBB0_1175:
	s_and_b64 vcc, exec, s[38:39]
	v_readlane_b32 s73, v255, 21
	s_cbranch_vccz .LBB0_1195
	s_waitcnt vmcnt(0)
	s_barrier
	s_mov_b64 s[38:39], exec
	v_readlane_b32 s6, v254, 3
	v_readlane_b32 s7, v254, 4
	s_and_b64 s[6:7], s[38:39], s[6:7]
	s_mov_b64 exec, s[6:7]
	s_cbranch_execz .LBB0_1194
	buffer_inv sc1
	v_readlane_b32 s20, v254, 61
	v_readlane_b32 s21, v254, 62
	v_readlane_b32 s6, v255, 60
	v_mov_b32_e32 v0, 1
	s_nop 3
	s_add_i32 s6, s6, 32
	global_atomic_add v49, v0, s[20:21]
	v_writelane_b32 v255, s6, 60
	s_sleep 6

.LBB0_1259:
	s_and_b64 vcc, exec, s[2:3]
	s_cbranch_vccz .LBB0_1279
	s_waitcnt vmcnt(0)
	s_barrier
	s_mov_b64 s[2:3], exec
	v_readlane_b32 s6, v254, 3
	v_readlane_b32 s7, v254, 4
	s_and_b64 s[6:7], s[2:3], s[6:7]
	s_mov_b64 exec, s[6:7]
	s_cbranch_execz .LBB0_1278
	buffer_inv sc1
	v_readlane_b32 s20, v254, 61
	v_readlane_b32 s21, v254, 62
	v_readlane_b32 s6, v255, 60
	v_mov_b32_e32 v0, 1
	s_nop 3
	s_add_i32 s6, s6, 32
	global_atomic_add v49, v0, s[20:21]
	v_writelane_b32 v255, s6, 60
	s_sleep 6

.LBB0_1379:
	s_and_b64 vcc, exec, s[2:3]
	s_cbranch_vccz .LBB0_1399
	s_waitcnt vmcnt(0)
	s_barrier
	s_mov_b64 s[2:3], exec
	v_readlane_b32 s8, v254, 3
	v_readlane_b32 s9, v254, 4
	s_and_b64 s[8:9], s[2:3], s[8:9]
	s_mov_b64 exec, s[8:9]
	s_cbranch_execz .LBB0_1398
	buffer_inv sc1
	v_readlane_b32 s20, v254, 61
	v_readlane_b32 s21, v254, 62
	v_readlane_b32 s6, v255, 60
	v_mov_b32_e32 v0, 1
	s_nop 3
	s_add_i32 s6, s6, 32
	global_atomic_add v49, v0, s[20:21]
	v_writelane_b32 v255, s6, 60
	s_sleep 6
